# speedup vs baseline: 1.0007x; 1.0007x over previous
; __device__ __forceinline__ bf16x8 cat44(s16x4 a, s16x4 b) { return (bf16x8){a[0], a[1], a[2], a[3], b[0], b[1], b[2], b[3]}; }
; __device__ __forceinline__ void attn_item(KP P, int l, bool isS, int b, int c, int hp, char* smem) {
;     ...
;     mx = fmaxf(mx, sx<16>(mx));
;     mx = fmaxf(mx, bperm(mx, lane ^ 32));
;     const float mn = fmaxf(mrow, mx);
;     const float alpha = __expf(mrow - mn);
;     mrow = mn;
;     lrow *= alpha;
;     bf16x8 pf[2];
; #pragma unroll
;     for (int kr = 0; kr < 2; ++kr) {
;       float p[8];
; #pragma unroll
;       for (int i = 0; i < 8; ++i) {
;         const int kb = kr * 2 + (i >> 2), j = i & 3;
;         const int jb = t * 64 + kb * 16 + fq * 4 + j;
;         const bool valid = (!isS) || (jb < 528);
;         p[i] = valid ? __expf(s[kb][j] - mn) : 0.f;
;         lrow += p[i];
;       }
;       pf[kr] = as_bf16x8(pack8(p));
;     }
; #pragma unroll
;     for (int db = 0; db < 8; ++db) {
; #pragma unroll
;       for (int j = 0; j < 4; ++j) o[db][j] *= alpha;
;     }
;     const int trr = fq * 4 + ((lane >> 2) & 3), trc = (lane & 3) * 4;
; #pragma unroll
;     for (int db = 0; db < 8; ++db) {
; #pragma unroll
;       for (int kr = 0; kr < 2; ++kr) {
;         const u16* p0 = Vs + (kr * 32 + trr) * 136 + db * 16 + trc;
;         const bf16x8 vf = cat44(ldtr(p0), ldtr(p0 + 16 * 136));
;         o[db] = __builtin_amdgcn_mfma_f32_16x16x32_bf16(vf, pf[kr], o[db], 0, 0, 0);
;       }
;     }
.Lfb_max:
	v_max3_f32 v88, v124, s34, v120
	v_max3_f32 v88, v88, v125, v122
	v_max3_f32 v88, v88, v123, v126
	v_max3_f32 v88, v88, v97, v98
	v_max3_f32 v88, v88, v99, v92
	v_max3_f32 v88, v88, v121, v94
	v_max3_f32 v88, v88, v95, v127
	v_max3_f32 v88, v88, v93, v119
	ds_swizzle_b32 v89, v88 offset:swizzle(SWAP,16)
	s_waitcnt lgkmcnt(0)
	v_max_f32_e32 v89, v89, v89
	v_max_f32_e32 v88, v88, v89
	ds_bpermute_b32 v89, v112, v88
	s_waitcnt lgkmcnt(0)
	ds_read_b64_tr_b16 v[160:161], v116 offset:17536
	ds_read_b64_tr_b16 v[162:163], v116 offset:21888
	ds_read_b64_tr_b16 v[164:165], v116 offset:26240
	ds_read_b64_tr_b16 v[166:167], v116 offset:30592
	ds_read_b64_tr_b16 v[168:169], v116 offset:17568
	ds_read_b64_tr_b16 v[170:171], v116 offset:21920
	ds_read_b64_tr_b16 v[172:173], v116 offset:26272
	ds_read_b64_tr_b16 v[174:175], v116 offset:30624
	ds_read_b64_tr_b16 v[176:177], v116 offset:17600
	ds_read_b64_tr_b16 v[178:179], v116 offset:21952
	ds_read_b64_tr_b16 v[180:181], v116 offset:26304
	ds_read_b64_tr_b16 v[182:183], v116 offset:30656
	ds_read_b64_tr_b16 v[184:185], v116 offset:17632
	ds_read_b64_tr_b16 v[186:187], v116 offset:21984
	ds_read_b64_tr_b16 v[192:193], v116 offset:26336
	ds_read_b64_tr_b16 v[194:195], v116 offset:30688
	v_max3_f32 v96, v118, v88, v89
	v_sub_f32_e32 v88, v118, v96
	v_mul_f32_e32 v88, 0x3fb8aa3b, v88
	v_exp_f32_e32 v118, v88
	v_sub_f32_e32 v196, v124, v96
	v_sub_f32_e32 v197, v120, v96
	v_sub_f32_e32 v198, v125, v96
	v_sub_f32_e32 v199, v122, v96
	v_sub_f32_e32 v200, v123, v96
	v_sub_f32_e32 v201, v126, v96
	v_sub_f32_e32 v202, v97, v96
	v_sub_f32_e32 v203, v98, v96
	v_sub_f32_e32 v204, v99, v96
	v_sub_f32_e32 v205, v92, v96
	v_sub_f32_e32 v206, v121, v96
	v_sub_f32_e32 v207, v94, v96
	v_sub_f32_e32 v208, v95, v96
	v_sub_f32_e32 v209, v127, v96
	v_sub_f32_e32 v210, v93, v96
	v_sub_f32_e32 v211, v119, v96
	v_mul_f32_e32 v196, 0x3fb8aa3b, v196
	v_mul_f32_e32 v197, 0x3fb8aa3b, v197
	v_mul_f32_e32 v198, 0x3fb8aa3b, v198
	v_mul_f32_e32 v199, 0x3fb8aa3b, v199
	v_mul_f32_e32 v200, 0x3fb8aa3b, v200
	v_mul_f32_e32 v201, 0x3fb8aa3b, v201
	v_mul_f32_e32 v202, 0x3fb8aa3b, v202
	v_mul_f32_e32 v203, 0x3fb8aa3b, v203
	v_mul_f32_e32 v204, 0x3fb8aa3b, v204
	v_mul_f32_e32 v205, 0x3fb8aa3b, v205
	v_mul_f32_e32 v206, 0x3fb8aa3b, v206
	v_mul_f32_e32 v207, 0x3fb8aa3b, v207
	v_mul_f32_e32 v208, 0x3fb8aa3b, v208
	v_mul_f32_e32 v209, 0x3fb8aa3b, v209
	v_mul_f32_e32 v210, 0x3fb8aa3b, v210
	v_mul_f32_e32 v211, 0x3fb8aa3b, v211
	v_exp_f32_e32 v196, v196
	v_exp_f32_e32 v197, v197
	v_exp_f32_e32 v198, v198
	v_exp_f32_e32 v199, v199
	v_exp_f32_e32 v200, v200
	v_exp_f32_e32 v201, v201
	v_exp_f32_e32 v202, v202
	v_exp_f32_e32 v203, v203
	v_exp_f32_e32 v204, v204
	v_exp_f32_e32 v205, v205
	v_exp_f32_e32 v206, v206
	v_exp_f32_e32 v207, v207
	v_exp_f32_e32 v208, v208
	v_exp_f32_e32 v209, v209
	v_exp_f32_e32 v210, v210
	v_exp_f32_e32 v211, v211
	s_nop 0
	v_fma_f32 v117, v117, v118, v196
	v_add_f32_e32 v117, v197, v117
	v_add_f32_e32 v117, v198, v117
	v_add_f32_e32 v117, v199, v117
	v_add_f32_e32 v117, v200, v117
	v_add_f32_e32 v117, v201, v117
	v_add_f32_e32 v117, v202, v117
	v_add_f32_e32 v117, v203, v117
	v_add_f32_e32 v117, v204, v117
	v_add_f32_e32 v117, v205, v117
	v_add_f32_e32 v117, v206, v117
	v_add_f32_e32 v117, v207, v117
	v_add_f32_e32 v117, v208, v117
	v_add_f32_e32 v117, v209, v117
	v_add_f32_e32 v117, v210, v117
	v_add_f32_e32 v117, v211, v117
	v_cvt_pk_bf16_f32 v88, v196, v197
	v_cvt_pk_bf16_f32 v89, v198, v199
	v_cvt_pk_bf16_f32 v90, v200, v201
	v_cvt_pk_bf16_f32 v91, v202, v203
	v_cvt_pk_bf16_f32 v92, v204, v205
	v_cvt_pk_bf16_f32 v93, v206, v207
	v_cvt_pk_bf16_f32 v94, v208, v209
	v_cvt_pk_bf16_f32 v95, v210, v211
	v_pk_mul_f32 v[58:59], v[58:59], v[118:119] op_sel_hi:[1,0]
	v_pk_mul_f32 v[56:57], v[56:57], v[118:119] op_sel_hi:[1,0]
	v_pk_mul_f32 v[46:47], v[46:47], v[118:119] op_sel_hi:[1,0]
	v_pk_mul_f32 v[44:45], v[44:45], v[118:119] op_sel_hi:[1,0]
	v_pk_mul_f32 v[54:55], v[54:55], v[118:119] op_sel_hi:[1,0]
	v_pk_mul_f32 v[52:53], v[52:53], v[118:119] op_sel_hi:[1,0]
	v_pk_mul_f32 v[74:75], v[74:75], v[118:119] op_sel_hi:[1,0]
	v_pk_mul_f32 v[72:73], v[72:73], v[118:119] op_sel_hi:[1,0]
	v_pk_mul_f32 v[78:79], v[78:79], v[118:119] op_sel_hi:[1,0]
	v_pk_mul_f32 v[76:77], v[76:77], v[118:119] op_sel_hi:[1,0]
	v_pk_mul_f32 v[70:71], v[70:71], v[118:119] op_sel_hi:[1,0]
	v_pk_mul_f32 v[68:69], v[68:69], v[118:119] op_sel_hi:[1,0]
	v_pk_mul_f32 v[82:83], v[82:83], v[118:119] op_sel_hi:[1,0]
	v_pk_mul_f32 v[80:81], v[80:81], v[118:119] op_sel_hi:[1,0]
	v_pk_mul_f32 v[86:87], v[86:87], v[118:119] op_sel_hi:[1,0]
	v_pk_mul_f32 v[84:85], v[84:85], v[118:119] op_sel_hi:[1,0]
	s_waitcnt lgkmcnt(0)
	s_barrier
	v_mfma_f32_16x16x32_bf16 v[56:59], v[128:131], v[88:91], v[56:59]
	v_mfma_f32_16x16x32_bf16 v[56:59], v[132:135], v[92:95], v[56:59]
	v_mfma_f32_16x16x32_bf16 v[44:47], v[136:139], v[88:91], v[44:47]
	v_mfma_f32_16x16x32_bf16 v[44:47], v[140:143], v[92:95], v[44:47]
	v_mfma_f32_16x16x32_bf16 v[52:55], v[144:147], v[88:91], v[52:55]
	v_mfma_f32_16x16x32_bf16 v[52:55], v[148:151], v[92:95], v[52:55]
	v_mfma_f32_16x16x32_bf16 v[72:75], v[152:155], v[88:91], v[72:75]
	v_mfma_f32_16x16x32_bf16 v[72:75], v[156:159], v[92:95], v[72:75]
	v_mfma_f32_16x16x32_bf16 v[76:79], v[160:163], v[88:91], v[76:79]
	v_mfma_f32_16x16x32_bf16 v[76:79], v[164:167], v[92:95], v[76:79]
	v_mfma_f32_16x16x32_bf16 v[68:71], v[168:171], v[88:91], v[68:71]
	v_mfma_f32_16x16x32_bf16 v[68:71], v[172:175], v[92:95], v[68:71]
	v_mfma_f32_16x16x32_bf16 v[80:83], v[176:179], v[88:91], v[80:83]
	v_mfma_f32_16x16x32_bf16 v[80:83], v[180:183], v[92:95], v[80:83]
	v_mfma_f32_16x16x32_bf16 v[84:87], v[184:187], v[88:91], v[84:87]
	v_mfma_f32_16x16x32_bf16 v[84:87], v[192:195], v[92:95], v[84:87]
	s_cmp_gt_u32 s1, 7
	s_cbranch_scc1 .LBB0_472
	v_mov_b32_e32 v118, v96
	s_branch .LBB0_476

; __device__ __forceinline__ bf16x8 cat44(s16x4 a, s16x4 b) { return (bf16x8){a[0], a[1], a[2], a[3], b[0], b[1], b[2], b[3]}; }
; __device__ __forceinline__ void attn_item(KP P, int l, bool isS, int b, int c, int hp, char* smem) {
;     ...
;     mx = fmaxf(mx, sx<16>(mx));
;     mx = fmaxf(mx, bperm(mx, lane ^ 32));
;     const float mn = fmaxf(mrow, mx);
;     const float alpha = __expf(mrow - mn);
;     mrow = mn;
;     lrow *= alpha;
;     bf16x8 pf[2];
; #pragma unroll
;     for (int kr = 0; kr < 2; ++kr) {
;       float p[8];
; #pragma unroll
;       for (int i = 0; i < 8; ++i) {
;         const int kb = kr * 2 + (i >> 2), j = i & 3;
;         const int jb = t * 64 + kb * 16 + fq * 4 + j;
;         const bool valid = (!isS) || (jb < 528);
;         p[i] = valid ? __expf(s[kb][j] - mn) : 0.f;
;         lrow += p[i];
;       }
;       pf[kr] = as_bf16x8(pack8(p));
;     }
; #pragma unroll
;     for (int db = 0; db < 8; ++db) {
; #pragma unroll
;       for (int j = 0; j < 4; ++j) o[db][j] *= alpha;
;     }
;     const int trr = fq * 4 + ((lane >> 2) & 3), trc = (lane & 3) * 4;
; #pragma unroll
;     for (int db = 0; db < 8; ++db) {
; #pragma unroll
;       for (int kr = 0; kr < 2; ++kr) {
;         const u16* p0 = Vs + (kr * 32 + trr) * 136 + db * 16 + trc;
;         const bf16x8 vf = cat44(ldtr(p0), ldtr(p0 + 16 * 136));
;         o[db] = __builtin_amdgcn_mfma_f32_16x16x32_bf16(vf, pf[kr], o[db], 0, 0, 0);
;       }
;     }
.Lat_max:
	v_max3_f32 v88, v124, s34, v120
	v_max3_f32 v88, v88, v125, v122
	v_max3_f32 v88, v88, v123, v126
	v_max3_f32 v88, v88, v97, v98
	v_max3_f32 v88, v88, v99, v92
	v_max3_f32 v88, v88, v121, v94
	v_max3_f32 v88, v88, v95, v127
	v_max3_f32 v88, v88, v93, v119
	ds_swizzle_b32 v89, v88 offset:swizzle(SWAP,16)
	s_waitcnt lgkmcnt(0)
	v_max_f32_e32 v89, v89, v89
	v_max_f32_e32 v88, v88, v89
	ds_bpermute_b32 v89, v113, v88
	s_waitcnt lgkmcnt(0)
	ds_read_b64_tr_b16 v[160:161], v116 offset:17536
	ds_read_b64_tr_b16 v[162:163], v116 offset:21888
	ds_read_b64_tr_b16 v[164:165], v116 offset:26240
	ds_read_b64_tr_b16 v[166:167], v116 offset:30592
	ds_read_b64_tr_b16 v[168:169], v116 offset:17568
	ds_read_b64_tr_b16 v[170:171], v116 offset:21920
	ds_read_b64_tr_b16 v[172:173], v116 offset:26272
	ds_read_b64_tr_b16 v[174:175], v116 offset:30624
	ds_read_b64_tr_b16 v[176:177], v116 offset:17600
	ds_read_b64_tr_b16 v[178:179], v116 offset:21952
	ds_read_b64_tr_b16 v[180:181], v116 offset:26304
	ds_read_b64_tr_b16 v[182:183], v116 offset:30656
	ds_read_b64_tr_b16 v[184:185], v116 offset:17632
	ds_read_b64_tr_b16 v[186:187], v116 offset:21984
	ds_read_b64_tr_b16 v[192:193], v116 offset:26336
	ds_read_b64_tr_b16 v[194:195], v116 offset:30688
	v_max3_f32 v96, v118, v88, v89
	v_sub_f32_e32 v88, v118, v96
	v_mul_f32_e32 v88, 0x3fb8aa3b, v88
	v_exp_f32_e32 v118, v88
	v_sub_f32_e32 v196, v124, v96
	v_sub_f32_e32 v197, v120, v96
	v_sub_f32_e32 v198, v125, v96
	v_sub_f32_e32 v199, v122, v96
	v_sub_f32_e32 v200, v123, v96
	v_sub_f32_e32 v201, v126, v96
	v_sub_f32_e32 v202, v97, v96
	v_sub_f32_e32 v203, v98, v96
	v_sub_f32_e32 v204, v99, v96
	v_sub_f32_e32 v205, v92, v96
	v_sub_f32_e32 v206, v121, v96
	v_sub_f32_e32 v207, v94, v96
	v_sub_f32_e32 v208, v95, v96
	v_sub_f32_e32 v209, v127, v96
	v_sub_f32_e32 v210, v93, v96
	v_sub_f32_e32 v211, v119, v96
	v_mul_f32_e32 v196, 0x3fb8aa3b, v196
	v_mul_f32_e32 v197, 0x3fb8aa3b, v197
	v_mul_f32_e32 v198, 0x3fb8aa3b, v198
	v_mul_f32_e32 v199, 0x3fb8aa3b, v199
	v_mul_f32_e32 v200, 0x3fb8aa3b, v200
	v_mul_f32_e32 v201, 0x3fb8aa3b, v201
	v_mul_f32_e32 v202, 0x3fb8aa3b, v202
	v_mul_f32_e32 v203, 0x3fb8aa3b, v203
	v_mul_f32_e32 v204, 0x3fb8aa3b, v204
	v_mul_f32_e32 v205, 0x3fb8aa3b, v205
	v_mul_f32_e32 v206, 0x3fb8aa3b, v206
	v_mul_f32_e32 v207, 0x3fb8aa3b, v207
	v_mul_f32_e32 v208, 0x3fb8aa3b, v208
	v_mul_f32_e32 v209, 0x3fb8aa3b, v209
	v_mul_f32_e32 v210, 0x3fb8aa3b, v210
	v_mul_f32_e32 v211, 0x3fb8aa3b, v211
	v_exp_f32_e32 v196, v196
	v_exp_f32_e32 v197, v197
	v_exp_f32_e32 v198, v198
	v_exp_f32_e32 v199, v199
	v_exp_f32_e32 v200, v200
	v_exp_f32_e32 v201, v201
	v_exp_f32_e32 v202, v202
	v_exp_f32_e32 v203, v203
	v_exp_f32_e32 v204, v204
	v_exp_f32_e32 v205, v205
	v_exp_f32_e32 v206, v206
	v_exp_f32_e32 v207, v207
	v_exp_f32_e32 v208, v208
	v_exp_f32_e32 v209, v209
	v_exp_f32_e32 v210, v210
	v_exp_f32_e32 v211, v211
	s_nop 0
	v_fma_f32 v117, v117, v118, v196
	v_add_f32_e32 v117, v197, v117
	v_add_f32_e32 v117, v198, v117
	v_add_f32_e32 v117, v199, v117
	v_add_f32_e32 v117, v200, v117
	v_add_f32_e32 v117, v201, v117
	v_add_f32_e32 v117, v202, v117
	v_add_f32_e32 v117, v203, v117
	v_add_f32_e32 v117, v204, v117
	v_add_f32_e32 v117, v205, v117
	v_add_f32_e32 v117, v206, v117
	v_add_f32_e32 v117, v207, v117
	v_add_f32_e32 v117, v208, v117
	v_add_f32_e32 v117, v209, v117
	v_add_f32_e32 v117, v210, v117
	v_add_f32_e32 v117, v211, v117
	v_cvt_pk_bf16_f32 v88, v196, v197
	v_cvt_pk_bf16_f32 v89, v198, v199
	v_cvt_pk_bf16_f32 v90, v200, v201
	v_cvt_pk_bf16_f32 v91, v202, v203
	v_cvt_pk_bf16_f32 v92, v204, v205
	v_cvt_pk_bf16_f32 v93, v206, v207
	v_cvt_pk_bf16_f32 v94, v208, v209
	v_cvt_pk_bf16_f32 v95, v210, v211
	v_pk_mul_f32 v[66:67], v[66:67], v[118:119] op_sel_hi:[1,0]
	v_pk_mul_f32 v[64:65], v[64:65], v[118:119] op_sel_hi:[1,0]
	v_pk_mul_f32 v[58:59], v[58:59], v[118:119] op_sel_hi:[1,0]
	v_pk_mul_f32 v[56:57], v[56:57], v[118:119] op_sel_hi:[1,0]
	v_pk_mul_f32 v[62:63], v[62:63], v[118:119] op_sel_hi:[1,0]
	v_pk_mul_f32 v[60:61], v[60:61], v[118:119] op_sel_hi:[1,0]
	v_pk_mul_f32 v[74:75], v[74:75], v[118:119] op_sel_hi:[1,0]
	v_pk_mul_f32 v[72:73], v[72:73], v[118:119] op_sel_hi:[1,0]
	v_pk_mul_f32 v[78:79], v[78:79], v[118:119] op_sel_hi:[1,0]
	v_pk_mul_f32 v[76:77], v[76:77], v[118:119] op_sel_hi:[1,0]
	v_pk_mul_f32 v[70:71], v[70:71], v[118:119] op_sel_hi:[1,0]
	v_pk_mul_f32 v[68:69], v[68:69], v[118:119] op_sel_hi:[1,0]
	v_pk_mul_f32 v[82:83], v[82:83], v[118:119] op_sel_hi:[1,0]
	v_pk_mul_f32 v[80:81], v[80:81], v[118:119] op_sel_hi:[1,0]
	v_pk_mul_f32 v[86:87], v[86:87], v[118:119] op_sel_hi:[1,0]
	v_pk_mul_f32 v[84:85], v[84:85], v[118:119] op_sel_hi:[1,0]
	s_waitcnt lgkmcnt(0)
	s_barrier
	v_mfma_f32_16x16x32_bf16 v[64:67], v[128:131], v[88:91], v[64:67]
	v_mfma_f32_16x16x32_bf16 v[64:67], v[132:135], v[92:95], v[64:67]
	v_mfma_f32_16x16x32_bf16 v[56:59], v[136:139], v[88:91], v[56:59]
	v_mfma_f32_16x16x32_bf16 v[56:59], v[140:143], v[92:95], v[56:59]
	v_mfma_f32_16x16x32_bf16 v[60:63], v[144:147], v[88:91], v[60:63]
	v_mfma_f32_16x16x32_bf16 v[60:63], v[148:151], v[92:95], v[60:63]
	v_mfma_f32_16x16x32_bf16 v[72:75], v[152:155], v[88:91], v[72:75]
	v_mfma_f32_16x16x32_bf16 v[72:75], v[156:159], v[92:95], v[72:75]
	v_mfma_f32_16x16x32_bf16 v[76:79], v[160:163], v[88:91], v[76:79]
	v_mfma_f32_16x16x32_bf16 v[76:79], v[164:167], v[92:95], v[76:79]
	v_mfma_f32_16x16x32_bf16 v[68:71], v[168:171], v[88:91], v[68:71]
	v_mfma_f32_16x16x32_bf16 v[68:71], v[172:175], v[92:95], v[68:71]
	v_mfma_f32_16x16x32_bf16 v[80:83], v[176:179], v[88:91], v[80:83]
	v_mfma_f32_16x16x32_bf16 v[80:83], v[180:183], v[92:95], v[80:83]
	v_mfma_f32_16x16x32_bf16 v[84:87], v[184:187], v[88:91], v[84:87]
	v_mfma_f32_16x16x32_bf16 v[84:87], v[192:195], v[92:95], v[84:87]
	s_cmp_gt_u32 s0, 7
	s_cbranch_scc1 .LBB0_513
	v_mov_b32_e32 v118, v96
	s_branch .LBB0_517
